# conv+gate pass: activations stored with default cache policy, streamed up-projection reads marked nt
# speedup vs baseline: 1.0316x; 1.0121x over previous
; DEVI float gelu_f(float x) { const float u = -2.302208198f * (x + 0.044715f * x * x * x); return x * __builtin_amdgcn_rcpf(1.f + __builtin_amdgcn_exp2f(u)); }
; DEVI void conv_gate_items(unsigned it_begin, unsigned it_end, unsigned it_step, const int rseg, const ConvP P) {
;     ...
;         for (int r0 = 0; r0 < rseg; r0 += 4) { h8 ra[4], rc[4]; float rsm[4], rsq[4];
; #pragma unroll
;             for (int k = 0; k < 4; ++k) { const int row = row0 + r0 + k; const h16* u_ = P.up + (size_t)row * DFF2 + j0; ra[k] = *(const h8*)u_; rc[k] = *(const h8*)(u_ + DFF); rsm[k] = P.st[2 * row]; rsq[k] = P.st[2 * row + 1]; }
; #pragma unroll
;             for (int k = 0; k < 4; ++k) { const int r = r0 + k; const float mean = rsm[k] * (1.f / DM), rstd = __builtin_amdgcn_rsqf(rsq[k] * (1.f / DM) - mean * mean + 1e-5f);
;                 const f4 cg0 = ((f4){(float)ra[k][0], (float)ra[k][1], (float)ra[k][2], (float)ra[k][3]} - cg0_ * mean) * rstd + dg0_, cg1 = ((f4){(float)ra[k][4], (float)ra[k][5], (float)ra[k][6], (float)ra[k][7]} - cg1_ * mean) * rstd + dg1_;
;                 const f4 cv0 = ((f4){(float)rc[k][0], (float)rc[k][1], (float)rc[k][2], (float)rc[k][3]} - cv0_ * mean) * rstd + dv0_, cv1 = ((f4){(float)rc[k][4], (float)rc[k][5], (float)rc[k][6], (float)rc[k][7]} - cv1_ * mean) * rstd + dv1_;
;                 const f4 g0 = bg0 + ag0 * wg0[0] + bg0_ * wg0[1] + cg0 * wg0[2], g1 = bg1 + ag1 * wg1[0] + bg1_ * wg1[1] + cg1 * wg1[2];
;                 const f4 v0 = bv0 + av0 * wv0[0] + bv0_ * wv0[1] + cv0 * wv0[2], v1 = bv1 + av1 * wv1[0] + bv1_ * wv1[1] + cv1 * wv1[2];
;                 h8 o;
; #pragma unroll
;                 for (int e = 0; e < 4; ++e) { o[e] = (h16)(gelu_f(g0[e]) * v0[e]); o[4 + e] = (h16)(gelu_f(g1[e]) * v1[e]); }
.LBB0_1277:
	v_lshl_add_u64 v[132:133], s[8:9], 0, v[164:165]
	v_add_co_u32_e32 v134, vcc, 0x366a1000, v132
	v_lshl_add_u64 v[140:141], s[8:9], 0, v[166:167]
	s_nop 0
	v_addc_co_u32_e32 v135, vcc, 0, v133, vcc
	global_load_dwordx4 v[170:173], v[134:135], off nt
	v_add_co_u32_e32 v134, vcc, 0x366a2000, v132
	v_lshl_add_u64 v[142:143], v[140:141], 0, s[92:93]
	s_nop 0
	v_addc_co_u32_e32 v135, vcc, 0, v133, vcc
	global_load_dwordx4 v[184:187], v[134:135], off offset:1536 nt
	v_add_co_u32_e32 v134, vcc, 0x366a3000, v132
	s_waitcnt vmcnt(12)
	v_pk_fma_f32 v[124:125], v[56:57], v[124:125], v[4:5]
	v_addc_co_u32_e32 v135, vcc, 0, v133, vcc
	global_load_dwordx4 v[156:159], v[134:135], off offset:3072 nt
	v_add_co_u32_e32 v134, vcc, 0x366a5000, v132
	s_waitcnt vmcnt(9)
	v_pk_fma_f32 v[124:125], v[72:73], v[112:113], v[124:125]
	v_addc_co_u32_e32 v135, vcc, 0, v133, vcc
	global_load_dwordx4 v[152:155], v[134:135], off offset:512 nt
	v_add_co_u32_e32 v134, vcc, 0x366a6000, v132
	v_pk_fma_f32 v[100:101], v[52:53], v[100:101], v[0:1]
	s_nop 0
	v_addc_co_u32_e32 v135, vcc, 0, v133, vcc
	global_load_dwordx4 v[148:151], v[134:135], off offset:2048 nt
	v_add_co_u32_e32 v134, vcc, 0x366a7000, v132
	v_pk_fma_f32 v[100:101], v[68:69], v[116:117], v[100:101]
	s_nop 0
	v_addc_co_u32_e32 v135, vcc, 0, v133, vcc
	global_load_dwordx4 v[144:147], v[134:135], off offset:3584 nt
	v_add_co_u32_e32 v134, vcc, 0x366a9000, v132
	v_pk_fma_f32 v[104:105], v[60:61], v[104:105], v[8:9]
	s_nop 0
	v_addc_co_u32_e32 v135, vcc, 0, v133, vcc
	v_add_co_u32_e32 v132, vcc, 0x366aa000, v132
	global_load_dwordx4 v[136:139], v[134:135], off offset:1024 nt
	s_nop 0
	v_addc_co_u32_e32 v133, vcc, 0, v133, vcc
	v_add_co_u32_e32 v140, vcc, 0x3f000, v140
	global_load_dwordx4 v[132:135], v[132:133], off offset:2560 nt
	s_nop 0
	v_addc_co_u32_e32 v141, vcc, 0, v141, vcc
	global_load_dwordx4 v[160:163], v[140:141], off
	s_nop 0
	global_load_dwordx4 v[140:143], v[142:143], off offset:16
	s_waitcnt vmcnt(15)
	v_pk_fma_f32 v[104:105], v[76:77], v[128:129], v[104:105]
	v_pk_fma_f32 v[126:127], v[58:59], v[126:127], v[6:7]
	v_pk_fma_f32 v[108:109], v[64:65], v[108:109], v[12:13]
	v_pk_fma_f32 v[102:103], v[54:55], v[102:103], v[2:3]
	s_waitcnt vmcnt(14)
	v_pk_fma_f32 v[108:109], v[80:81], v[120:121], v[108:109]
	v_pk_fma_f32 v[106:107], v[62:63], v[106:107], v[10:11]
	s_mov_b32 s0, 0x4d1a1000
	s_waitcnt vmcnt(9)
	v_cvt_f32_f16_e32 v174, v170
	v_cvt_f32_f16_sdwa v175, v170 dst_sel:DWORD dst_unused:UNUSED_PAD src0_sel:WORD_1
	v_cvt_f32_f16_e32 v170, v171
	v_cvt_f32_f16_sdwa v171, v171 dst_sel:DWORD dst_unused:UNUSED_PAD src0_sel:WORD_1
	s_waitcnt vmcnt(1)
	v_pk_mul_f32 v[160:161], v[160:161], s[82:83] op_sel_hi:[1,0]
	s_nop 0
	v_fma_f32 v48, -v160, v160, v161
	v_add_f32_e32 v48, 0x3727c5ac, v48
	v_rsq_f32_e32 v48, v48
	v_pk_fma_f32 v[170:171], v[22:23], v[160:161], v[170:171] op_sel_hi:[1,0,1]
	v_pk_fma_f32 v[176:177], v[20:21], v[160:161], v[174:175] op_sel_hi:[1,0,1] neg_lo:[1,0,0] neg_hi:[1,0,0]
	v_pk_fma_f32 v[174:175], v[170:171], v[48:49], v[38:39] op_sel_hi:[1,0,1]
	v_cvt_f32_f16_e32 v170, v172
	v_cvt_f32_f16_sdwa v171, v172 dst_sel:DWORD dst_unused:UNUSED_PAD src0_sel:WORD_1
	v_cvt_f32_f16_e32 v172, v173
	v_cvt_f32_f16_sdwa v173, v173 dst_sel:DWORD dst_unused:UNUSED_PAD src0_sel:WORD_1
	v_pk_fma_f32 v[182:183], v[176:177], v[48:49], v[36:37] op_sel_hi:[1,0,1]
	v_pk_fma_f32 v[176:177], v[16:17], v[160:161], v[170:171] op_sel_hi:[1,0,1] neg_lo:[1,0,0] neg_hi:[1,0,0]
	v_pk_fma_f32 v[124:125], v[88:89], v[182:183], v[124:125]
	v_pk_fma_f32 v[170:171], v[18:19], v[160:161], v[172:173] op_sel_hi:[1,0,1]
	v_pk_fma_f32 v[178:179], v[176:177], v[48:49], v[32:33] op_sel_hi:[1,0,1]
	v_cvt_f32_f16_e32 v172, v184
	v_cvt_f32_f16_sdwa v173, v184 dst_sel:DWORD dst_unused:UNUSED_PAD src0_sel:WORD_1
	v_cvt_f32_f16_e32 v176, v185
	v_cvt_f32_f16_sdwa v177, v185 dst_sel:DWORD dst_unused:UNUSED_PAD src0_sel:WORD_1
	v_cvt_f32_f16_e32 v184, v187
	v_pk_fma_f32 v[180:181], v[28:29], v[160:161], v[172:173] op_sel_hi:[1,0,1] neg_lo:[1,0,0] neg_hi:[1,0,0]
	v_cvt_f32_f16_sdwa v185, v187 dst_sel:DWORD dst_unused:UNUSED_PAD src0_sel:WORD_1
	v_pk_fma_f32 v[172:173], v[30:31], v[160:161], v[176:177] op_sel_hi:[1,0,1]
	v_cvt_f32_f16_e32 v176, v186
	v_cvt_f32_f16_sdwa v177, v186 dst_sel:DWORD dst_unused:UNUSED_PAD src0_sel:WORD_1
	v_pk_fma_f32 v[170:171], v[170:171], v[48:49], v[34:35] op_sel_hi:[1,0,1]
	v_pk_fma_f32 v[172:173], v[172:173], v[48:49], v[46:47] op_sel_hi:[1,0,1]
	v_pk_fma_f32 v[180:181], v[180:181], v[48:49], v[44:45] op_sel_hi:[1,0,1]
	v_pk_fma_f32 v[176:177], v[24:25], v[160:161], v[176:177] op_sel_hi:[1,0,1] neg_lo:[1,0,0] neg_hi:[1,0,0]
	v_pk_fma_f32 v[160:161], v[26:27], v[160:161], v[184:185] op_sel_hi:[1,0,1]
	v_pk_fma_f32 v[176:177], v[176:177], v[48:49], v[40:41] op_sel_hi:[1,0,1]
	v_pk_fma_f32 v[160:161], v[160:161], v[48:49], v[42:43] op_sel_hi:[1,0,1]
	v_mul_f32_e32 v48, 0x3d372713, v124
	v_mul_f32_e32 v48, v124, v48
	v_fma_f32 v48, v124, v48, v124
	v_mul_f32_e32 v48, 0xc0135761, v48
	v_exp_f32_e32 v48, v48
	v_pk_fma_f32 v[100:101], v[84:85], v[178:179], v[100:101]
	v_pk_fma_f32 v[104:105], v[92:93], v[176:177], v[104:105]
	v_pk_fma_f32 v[108:109], v[96:97], v[180:181], v[108:109]
	v_add_f32_e32 v48, 1.0, v48
	v_rcp_f32_e32 v184, v48
	v_mul_f32_e32 v48, 0x3d372713, v125
	v_mul_f32_e32 v48, v125, v48
	v_fma_f32 v48, v125, v48, v125
	v_mul_f32_e32 v48, 0xc0135761, v48
	v_exp_f32_e32 v48, v48
	s_nop 0
	v_add_f32_e32 v48, 1.0, v48
	v_rcp_f32_e32 v185, v48
	v_mul_f32_e32 v48, 0x3d372713, v100
	v_mul_f32_e32 v48, v100, v48
	v_fma_f32 v48, v100, v48, v100
	v_mul_f32_e32 v48, 0xc0135761, v48
	v_exp_f32_e32 v48, v48
; DEVI float gelu_f(float x) { const float u = -2.302208198f * (x + 0.044715f * x * x * x); return x * __builtin_amdgcn_rcpf(1.f + __builtin_amdgcn_exp2f(u)); }
; DEVI void conv_gate_items(unsigned it_begin, unsigned it_end, unsigned it_step, const int rseg, const ConvP P) {
;     ...
;             for (int k = 0; k < 4; ++k) { const int r = r0 + k; const float mean = rsm[k] * (1.f / DM), rstd = __builtin_amdgcn_rsqf(rsq[k] * (1.f / DM) - mean * mean + 1e-5f);
;                 const f4 cg0 = ((f4){(float)ra[k][0], (float)ra[k][1], (float)ra[k][2], (float)ra[k][3]} - cg0_ * mean) * rstd + dg0_, cg1 = ((f4){(float)ra[k][4], (float)ra[k][5], (float)ra[k][6], (float)ra[k][7]} - cg1_ * mean) * rstd + dg1_;
;                 const f4 cv0 = ((f4){(float)rc[k][0], (float)rc[k][1], (float)rc[k][2], (float)rc[k][3]} - cv0_ * mean) * rstd + dv0_, cv1 = ((f4){(float)rc[k][4], (float)rc[k][5], (float)rc[k][6], (float)rc[k][7]} - cv1_ * mean) * rstd + dv1_;
;                 const f4 g0 = bg0 + ag0 * wg0[0] + bg0_ * wg0[1] + cg0 * wg0[2], g1 = bg1 + ag1 * wg1[0] + bg1_ * wg1[1] + cg1 * wg1[2];
;                 const f4 v0 = bv0 + av0 * wv0[0] + bv0_ * wv0[1] + cv0 * wv0[2], v1 = bv1 + av1 * wv1[0] + bv1_ * wv1[1] + cv1 * wv1[2];
;                 h8 o;
; #pragma unroll
;                 for (int e = 0; e < 4; ++e) { o[e] = (h16)(gelu_f(g0[e]) * v0[e]); o[4 + e] = (h16)(gelu_f(g1[e]) * v1[e]); }
	v_pk_mul_f32 v[184:185], v[124:125], v[184:185]
	v_pk_fma_f32 v[124:125], v[66:67], v[110:111], v[14:15]
	v_pk_mul_f32 v[108:109], v[108:109], v[184:185]
	v_add_f32_e32 v48, 1.0, v48
	v_rcp_f32_e32 v110, v48
	v_mul_f32_e32 v48, 0x3d372713, v101
	v_mul_f32_e32 v48, v101, v48
	v_fma_f32 v48, v101, v48, v101
	v_mul_f32_e32 v48, 0xc0135761, v48
	v_exp_f32_e32 v48, v48
	v_cvt_pk_f16_f32 v108, v108, v109
	v_lshl_add_u64 v[184:185], s[8:9], 0, v[168:169]
	v_add_f32_e32 v48, 1.0, v48
	v_rcp_f32_e32 v111, v48
	s_nop 0
	v_pk_mul_f32 v[100:101], v[100:101], v[110:111]
	s_nop 0
	v_pk_mul_f32 v[100:101], v[104:105], v[100:101]
	s_nop 0
	v_cvt_pk_f16_f32 v110, v100, v101
	v_pk_fma_f32 v[100:101], v[74:75], v[114:115], v[126:127]
	s_nop 0
	v_pk_fma_f32 v[100:101], v[90:91], v[174:175], v[100:101]
	s_nop 0
	v_mul_f32_e32 v48, 0x3d372713, v100
	v_mul_f32_e32 v48, v100, v48
	v_fma_f32 v48, v100, v48, v100
	v_mul_f32_e32 v48, 0xc0135761, v48
	v_exp_f32_e32 v48, v48
	s_nop 0
	v_add_f32_e32 v48, 1.0, v48
	v_rcp_f32_e32 v104, v48
	v_mul_f32_e32 v48, 0x3d372713, v101
	v_mul_f32_e32 v48, v101, v48
	v_fma_f32 v48, v101, v48, v101
	v_mul_f32_e32 v48, 0xc0135761, v48
	v_exp_f32_e32 v48, v48
	s_nop 0
	v_add_f32_e32 v48, 1.0, v48
	v_rcp_f32_e32 v105, v48
	s_nop 0
	v_pk_mul_f32 v[100:101], v[100:101], v[104:105]
	v_pk_fma_f32 v[104:105], v[82:83], v[122:123], v[124:125]
	s_nop 0
	v_pk_fma_f32 v[104:105], v[98:99], v[172:173], v[104:105]
	s_nop 0
	v_pk_mul_f32 v[100:101], v[104:105], v[100:101]
	v_cvt_f32_f16_e32 v104, v157
	v_cvt_pk_f16_f32 v109, v100, v101
	v_pk_fma_f32 v[100:101], v[70:71], v[118:119], v[102:103]
	v_cvt_f32_f16_sdwa v105, v157 dst_sel:DWORD dst_unused:UNUSED_PAD src0_sel:WORD_1
	v_pk_fma_f32 v[100:101], v[86:87], v[170:171], v[100:101]
	s_nop 0
	v_mul_f32_e32 v48, 0x3d372713, v100
	v_mul_f32_e32 v48, v100, v48
	v_fma_f32 v48, v100, v48, v100
	v_mul_f32_e32 v48, 0xc0135761, v48
	v_exp_f32_e32 v48, v48
	s_nop 0
	v_add_f32_e32 v48, 1.0, v48
	v_rcp_f32_e32 v102, v48
	v_mul_f32_e32 v48, 0x3d372713, v101
	v_mul_f32_e32 v48, v101, v48
	v_fma_f32 v48, v101, v48, v101
	v_mul_f32_e32 v48, 0xc0135761, v48
	v_exp_f32_e32 v48, v48
	s_nop 0
	v_add_f32_e32 v48, 1.0, v48
	v_rcp_f32_e32 v103, v48
	s_nop 0
	v_pk_mul_f32 v[100:101], v[100:101], v[102:103]
	v_pk_fma_f32 v[102:103], v[78:79], v[130:131], v[106:107]
	s_nop 0
	v_pk_fma_f32 v[102:103], v[94:95], v[160:161], v[102:103]
	s_nop 0
	v_pk_mul_f32 v[100:101], v[102:103], v[100:101]
	v_cvt_f32_f16_e32 v102, v156
	v_cvt_pk_f16_f32 v111, v100, v101
	v_pk_mul_f32 v[100:101], v[162:163], s[82:83] op_sel_hi:[1,0]
	v_cvt_f32_f16_sdwa v103, v156 dst_sel:DWORD dst_unused:UNUSED_PAD src0_sel:WORD_1
	v_fma_f32 v48, -v100, v100, v101
	v_add_f32_e32 v48, 0x3727c5ac, v48
	v_rsq_f32_e32 v48, v48
	v_pk_fma_f32 v[102:103], v[20:21], v[100:101], v[102:103] op_sel_hi:[1,0,1] neg_lo:[1,0,0] neg_hi:[1,0,0]
	v_pk_fma_f32 v[104:105], v[22:23], v[100:101], v[104:105] op_sel_hi:[1,0,1]
	v_pk_fma_f32 v[188:189], v[102:103], v[48:49], v[36:37] op_sel_hi:[1,0,1]
	v_pk_fma_f32 v[162:163], v[104:105], v[48:49], v[38:39] op_sel_hi:[1,0,1]
	v_cvt_f32_f16_e32 v102, v158
	v_cvt_f32_f16_sdwa v103, v158 dst_sel:DWORD dst_unused:UNUSED_PAD src0_sel:WORD_1
	v_cvt_f32_f16_e32 v104, v159
	v_cvt_f32_f16_sdwa v105, v159 dst_sel:DWORD dst_unused:UNUSED_PAD src0_sel:WORD_1
	v_pk_fma_f32 v[102:103], v[16:17], v[100:101], v[102:103] op_sel_hi:[1,0,1] neg_lo:[1,0,0] neg_hi:[1,0,0]
	s_nop 0
	v_pk_fma_f32 v[186:187], v[102:103], v[48:49], v[32:33] op_sel_hi:[1,0,1]
	v_pk_fma_f32 v[104:105], v[18:19], v[100:101], v[104:105] op_sel_hi:[1,0,1]
	v_cvt_f32_f16_e32 v102, v152
	v_pk_fma_f32 v[156:157], v[104:105], v[48:49], v[34:35] op_sel_hi:[1,0,1]
	v_cvt_f32_f16_sdwa v103, v152 dst_sel:DWORD dst_unused:UNUSED_PAD src0_sel:WORD_1
	v_cvt_f32_f16_e32 v104, v153
	v_cvt_f32_f16_sdwa v105, v153 dst_sel:DWORD dst_unused:UNUSED_PAD src0_sel:WORD_1
	v_pk_fma_f32 v[102:103], v[28:29], v[100:101], v[102:103] op_sel_hi:[1,0,1] neg_lo:[1,0,0] neg_hi:[1,0,0]
	s_nop 0
	v_pk_fma_f32 v[190:191], v[102:103], v[48:49], v[44:45] op_sel_hi:[1,0,1]
	v_pk_fma_f32 v[104:105], v[30:31], v[100:101], v[104:105] op_sel_hi:[1,0,1]
	v_cvt_f32_f16_e32 v102, v154
	v_pk_fma_f32 v[158:159], v[104:105], v[48:49], v[46:47] op_sel_hi:[1,0,1]
	v_cvt_f32_f16_sdwa v103, v154 dst_sel:DWORD dst_unused:UNUSED_PAD src0_sel:WORD_1
	v_cvt_f32_f16_e32 v104, v155
	v_cvt_f32_f16_sdwa v105, v155 dst_sel:DWORD dst_unused:UNUSED_PAD src0_sel:WORD_1
	v_pk_fma_f32 v[102:103], v[24:25], v[100:101], v[102:103] op_sel_hi:[1,0,1] neg_lo:[1,0,0] neg_hi:[1,0,0]
	s_nop 0
	v_pk_fma_f32 v[154:155], v[102:103], v[48:49], v[40:41] op_sel_hi:[1,0,1]
	v_pk_fma_f32 v[100:101], v[26:27], v[100:101], v[104:105] op_sel_hi:[1,0,1]
	s_nop 0
	v_pk_fma_f32 v[152:153], v[100:101], v[48:49], v[42:43] op_sel_hi:[1,0,1]
	v_pk_fma_f32 v[100:101], v[56:57], v[112:113], v[4:5]
	v_cvt_f32_f16_e32 v112, v147
	v_pk_fma_f32 v[100:101], v[72:73], v[182:183], v[100:101]
	v_cvt_f32_f16_sdwa v113, v147 dst_sel:DWORD dst_unused:UNUSED_PAD src0_sel:WORD_1
	v_pk_fma_f32 v[100:101], v[88:89], v[188:189], v[100:101]
	s_nop 0
	v_mul_f32_e32 v48, 0x3d372713, v100
	v_mul_f32_e32 v48, v100, v48
	v_fma_f32 v48, v100, v48, v100
	v_mul_f32_e32 v48, 0xc0135761, v48
	v_exp_f32_e32 v48, v48
	s_nop 0
	v_add_f32_e32 v48, 1.0, v48
	v_rcp_f32_e32 v102, v48
	v_mul_f32_e32 v48, 0x3d372713, v101
	v_mul_f32_e32 v48, v101, v48
	v_fma_f32 v48, v101, v48, v101
	v_mul_f32_e32 v48, 0xc0135761, v48
	v_exp_f32_e32 v48, v48
	s_nop 0
	v_add_f32_e32 v48, 1.0, v48
	v_rcp_f32_e32 v103, v48
	s_nop 0
	v_pk_mul_f32 v[100:101], v[100:101], v[102:103]
	v_pk_fma_f32 v[102:103], v[64:65], v[120:121], v[12:13]
; DEVI float gelu_f(float x) { const float u = -2.302208198f * (x + 0.044715f * x * x * x); return x * __builtin_amdgcn_rcpf(1.f + __builtin_amdgcn_exp2f(u)); }
; DEVI void conv_gate_items(unsigned it_begin, unsigned it_end, unsigned it_step, const int rseg, const ConvP P) {
;     ...
;             for (int k = 0; k < 4; ++k) { const int r = r0 + k; const float mean = rsm[k] * (1.f / DM), rstd = __builtin_amdgcn_rsqf(rsq[k] * (1.f / DM) - mean * mean + 1e-5f);
;                 const f4 cg0 = ((f4){(float)ra[k][0], (float)ra[k][1], (float)ra[k][2], (float)ra[k][3]} - cg0_ * mean) * rstd + dg0_, cg1 = ((f4){(float)ra[k][4], (float)ra[k][5], (float)ra[k][6], (float)ra[k][7]} - cg1_ * mean) * rstd + dg1_;
;                 const f4 cv0 = ((f4){(float)rc[k][0], (float)rc[k][1], (float)rc[k][2], (float)rc[k][3]} - cv0_ * mean) * rstd + dv0_, cv1 = ((f4){(float)rc[k][4], (float)rc[k][5], (float)rc[k][6], (float)rc[k][7]} - cv1_ * mean) * rstd + dv1_;
;                 const f4 g0 = bg0 + ag0 * wg0[0] + bg0_ * wg0[1] + cg0 * wg0[2], g1 = bg1 + ag1 * wg1[0] + bg1_ * wg1[1] + cg1 * wg1[2];
;                 const f4 v0 = bv0 + av0 * wv0[0] + bv0_ * wv0[1] + cv0 * wv0[2], v1 = bv1 + av1 * wv1[0] + bv1_ * wv1[1] + cv1 * wv1[2];
;                 h8 o;
; #pragma unroll
;                 for (int e = 0; e < 4; ++e) { o[e] = (h16)(gelu_f(g0[e]) * v0[e]); o[4 + e] = (h16)(gelu_f(g1[e]) * v1[e]); }
;                 __builtin_nontemporal_store(o, (h8*)(ar + (size_t)r * DFF));
	s_nop 0
	v_pk_fma_f32 v[102:103], v[80:81], v[180:181], v[102:103]
	s_nop 0
	v_pk_fma_f32 v[102:103], v[96:97], v[190:191], v[102:103]
	s_nop 0
	v_pk_mul_f32 v[100:101], v[102:103], v[100:101]
	v_pk_fma_f32 v[102:103], v[52:53], v[116:117], v[0:1]
	v_cvt_pk_f16_f32 v100, v100, v101
	v_pk_fma_f32 v[102:103], v[68:69], v[178:179], v[102:103]
	s_nop 0
	v_pk_fma_f32 v[102:103], v[84:85], v[186:187], v[102:103]
	s_nop 0
	v_mul_f32_e32 v48, 0x3d372713, v102
	v_mul_f32_e32 v48, v102, v48
	v_fma_f32 v48, v102, v48, v102
	v_mul_f32_e32 v48, 0xc0135761, v48
	v_exp_f32_e32 v48, v48
	s_nop 0
	v_add_f32_e32 v48, 1.0, v48
	v_rcp_f32_e32 v104, v48
	v_mul_f32_e32 v48, 0x3d372713, v103
	v_mul_f32_e32 v48, v103, v48
	v_fma_f32 v48, v103, v48, v103
	v_mul_f32_e32 v48, 0xc0135761, v48
	v_exp_f32_e32 v48, v48
	s_nop 0
	v_add_f32_e32 v48, 1.0, v48
	v_rcp_f32_e32 v105, v48
	s_nop 0
	v_pk_mul_f32 v[102:103], v[102:103], v[104:105]
	v_pk_fma_f32 v[104:105], v[60:61], v[128:129], v[8:9]
	s_nop 0
	v_pk_fma_f32 v[104:105], v[76:77], v[176:177], v[104:105]
	s_nop 0
	v_pk_fma_f32 v[104:105], v[92:93], v[154:155], v[104:105]
	s_nop 0
	v_pk_mul_f32 v[102:103], v[104:105], v[102:103]
	v_pk_fma_f32 v[104:105], v[58:59], v[114:115], v[6:7]
	v_cvt_pk_f16_f32 v102, v102, v103
	v_pk_fma_f32 v[104:105], v[74:75], v[174:175], v[104:105]
	s_nop 0
	v_pk_fma_f32 v[104:105], v[90:91], v[162:163], v[104:105]
	s_nop 0
	v_mul_f32_e32 v48, 0x3d372713, v104
	v_mul_f32_e32 v48, v104, v48
	v_fma_f32 v48, v104, v48, v104
	v_mul_f32_e32 v48, 0xc0135761, v48
	v_exp_f32_e32 v48, v48
	s_nop 0
	v_add_f32_e32 v48, 1.0, v48
	v_rcp_f32_e32 v106, v48
	v_mul_f32_e32 v48, 0x3d372713, v105
	v_mul_f32_e32 v48, v105, v48
	v_fma_f32 v48, v105, v48, v105
	v_mul_f32_e32 v48, 0xc0135761, v48
	v_exp_f32_e32 v48, v48
	s_nop 0
	v_add_f32_e32 v48, 1.0, v48
	v_rcp_f32_e32 v107, v48
	s_nop 0
	v_pk_mul_f32 v[104:105], v[104:105], v[106:107]
	v_pk_fma_f32 v[106:107], v[66:67], v[122:123], v[14:15]
	s_nop 0
	v_pk_fma_f32 v[106:107], v[82:83], v[172:173], v[106:107]
	s_nop 0
	v_pk_fma_f32 v[106:107], v[98:99], v[158:159], v[106:107]
	s_nop 0
	v_pk_mul_f32 v[104:105], v[106:107], v[104:105]
	s_nop 0
	v_cvt_pk_f16_f32 v101, v104, v105
	v_pk_fma_f32 v[104:105], v[54:55], v[118:119], v[2:3]
	s_nop 0
	v_pk_fma_f32 v[104:105], v[70:71], v[170:171], v[104:105]
	s_nop 0
	v_pk_fma_f32 v[104:105], v[86:87], v[156:157], v[104:105]
	s_nop 0
	v_mul_f32_e32 v48, 0x3d372713, v104
	v_mul_f32_e32 v48, v104, v48
	v_fma_f32 v48, v104, v48, v104
	v_mul_f32_e32 v48, 0xc0135761, v48
	v_exp_f32_e32 v48, v48
	s_nop 0
	v_add_f32_e32 v48, 1.0, v48
	v_rcp_f32_e32 v106, v48
	v_mul_f32_e32 v48, 0x3d372713, v105
	v_mul_f32_e32 v48, v105, v48
	v_fma_f32 v48, v105, v48, v105
	v_mul_f32_e32 v48, 0xc0135761, v48
	v_exp_f32_e32 v48, v48
	s_nop 0
	v_add_f32_e32 v48, 1.0, v48
	v_rcp_f32_e32 v107, v48
	s_nop 0
	v_pk_mul_f32 v[104:105], v[104:105], v[106:107]
	v_pk_fma_f32 v[106:107], v[62:63], v[130:131], v[10:11]
	s_nop 0
	v_pk_fma_f32 v[106:107], v[78:79], v[160:161], v[106:107]
	s_nop 0
	v_pk_fma_f32 v[106:107], v[94:95], v[152:153], v[106:107]
	s_nop 0
	v_pk_mul_f32 v[104:105], v[106:107], v[104:105]
	v_cvt_f32_f16_e32 v106, v144
	v_cvt_pk_f16_f32 v103, v104, v105
	v_add_co_u32_e32 v104, vcc, s0, v184
	s_mov_b32 s0, 0x4d1a2000
	s_nop 0
	v_addc_co_u32_e32 v105, vcc, 0, v185, vcc
	global_store_dwordx4 v[104:105], v[108:111], off
	v_add_co_u32_e32 v104, vcc, s0, v184
	v_cvt_f32_f16_sdwa v107, v144 dst_sel:DWORD dst_unused:UNUSED_PAD src0_sel:WORD_1
	s_nop 0
	v_addc_co_u32_e32 v105, vcc, 0, v185, vcc
	global_store_dwordx4 v[104:105], v[100:103], off offset:1536
	s_waitcnt vmcnt(2)
	v_pk_mul_f32 v[104:105], v[140:141], s[82:83] op_sel_hi:[1,0]
	v_cvt_f32_f16_e32 v108, v145
	v_fma_f32 v48, -v104, v104, v105
	v_add_f32_e32 v48, 0x3727c5ac, v48
	v_cvt_f32_f16_e32 v100, v148
	v_cvt_f32_f16_sdwa v101, v148 dst_sel:DWORD dst_unused:UNUSED_PAD src0_sel:WORD_1
	v_cvt_f32_f16_e32 v102, v149
	v_cvt_f32_f16_sdwa v103, v149 dst_sel:DWORD dst_unused:UNUSED_PAD src0_sel:WORD_1
	v_cvt_f32_f16_sdwa v109, v145 dst_sel:DWORD dst_unused:UNUSED_PAD src0_sel:WORD_1
	v_rsq_f32_e32 v48, v48
	v_pk_fma_f32 v[100:101], v[20:21], v[104:105], v[100:101] op_sel_hi:[1,0,1] neg_lo:[1,0,0] neg_hi:[1,0,0]
	v_pk_fma_f32 v[102:103], v[22:23], v[104:105], v[102:103] op_sel_hi:[1,0,1]
	v_pk_fma_f32 v[106:107], v[28:29], v[104:105], v[106:107] op_sel_hi:[1,0,1] neg_lo:[1,0,0] neg_hi:[1,0,0]
	v_pk_fma_f32 v[108:109], v[30:31], v[104:105], v[108:109] op_sel_hi:[1,0,1]
	v_pk_fma_f32 v[126:127], v[102:103], v[48:49], v[38:39] op_sel_hi:[1,0,1]
	v_pk_fma_f32 v[124:125], v[100:101], v[48:49], v[36:37] op_sel_hi:[1,0,1]
	v_cvt_f32_f16_e32 v100, v150
	v_cvt_f32_f16_sdwa v101, v150 dst_sel:DWORD dst_unused:UNUSED_PAD src0_sel:WORD_1
	v_cvt_f32_f16_e32 v102, v151
	v_cvt_f32_f16_sdwa v103, v151 dst_sel:DWORD dst_unused:UNUSED_PAD src0_sel:WORD_1
	v_pk_fma_f32 v[110:111], v[108:109], v[48:49], v[46:47] op_sel_hi:[1,0,1]
	v_pk_fma_f32 v[108:109], v[106:107], v[48:49], v[44:45] op_sel_hi:[1,0,1]
	v_cvt_f32_f16_e32 v106, v146
	v_cvt_f32_f16_sdwa v107, v146 dst_sel:DWORD dst_unused:UNUSED_PAD src0_sel:WORD_1
	v_pk_fma_f32 v[100:101], v[16:17], v[104:105], v[100:101] op_sel_hi:[1,0,1] neg_lo:[1,0,0] neg_hi:[1,0,0]
	v_pk_fma_f32 v[102:103], v[18:19], v[104:105], v[102:103] op_sel_hi:[1,0,1]
	v_pk_fma_f32 v[100:101], v[100:101], v[48:49], v[32:33] op_sel_hi:[1,0,1]
	v_pk_fma_f32 v[114:115], v[24:25], v[104:105], v[106:107] op_sel_hi:[1,0,1] neg_lo:[1,0,0] neg_hi:[1,0,0]
	v_pk_fma_f32 v[104:105], v[26:27], v[104:105], v[112:113] op_sel_hi:[1,0,1]
	v_pk_fma_f32 v[112:113], v[56:57], v[182:183], v[4:5]
; DEVI float gelu_f(float x) { const float u = -2.302208198f * (x + 0.044715f * x * x * x); return x * __builtin_amdgcn_rcpf(1.f + __builtin_amdgcn_exp2f(u)); }
; DEVI void conv_gate_items(unsigned it_begin, unsigned it_end, unsigned it_step, const int rseg, const ConvP P) {
;     ...
;                 const f4 g0 = bg0 + ag0 * wg0[0] + bg0_ * wg0[1] + cg0 * wg0[2], g1 = bg1 + ag1 * wg1[0] + bg1_ * wg1[1] + cg1 * wg1[2];
;                 const f4 v0 = bv0 + av0 * wv0[0] + bv0_ * wv0[1] + cv0 * wv0[2], v1 = bv1 + av1 * wv1[0] + bv1_ * wv1[1] + cv1 * wv1[2];
;                 h8 o;
; #pragma unroll
;                 for (int e = 0; e < 4; ++e) { o[e] = (h16)(gelu_f(g0[e]) * v0[e]); o[4 + e] = (h16)(gelu_f(g1[e]) * v1[e]); }
;                 __builtin_nontemporal_store(o, (h8*)(ar + (size_t)r * DFF));
;                 const int t = t0 + r;
;                 if (t >= T - 2) { float* so = P.pfc + (samp ? P.sdelta + ((size_t)bb * 2 + (t - (T - 2))) * DFF2 : ((size_t)(row0 >> 11) * 2 + (t - (T - 2))) * DFF2) + j0;
;                     *(f4*)so = cg0; *(f4*)(so + 4) = cg1; *(f4*)(so + DFF) = cv0; *(f4*)(so + DFF + 4) = cv1; }
	v_pk_fma_f32 v[102:103], v[102:103], v[48:49], v[34:35] op_sel_hi:[1,0,1]
	v_pk_fma_f32 v[112:113], v[72:73], v[188:189], v[112:113]
	v_pk_fma_f32 v[106:107], v[104:105], v[48:49], v[42:43] op_sel_hi:[1,0,1]
	v_pk_fma_f32 v[112:113], v[88:89], v[124:125], v[112:113]
	v_pk_fma_f32 v[104:105], v[114:115], v[48:49], v[40:41] op_sel_hi:[1,0,1]
	v_mul_f32_e32 v48, 0x3d372713, v112
	v_mul_f32_e32 v48, v112, v48
	v_fma_f32 v48, v112, v48, v112
	v_mul_f32_e32 v48, 0xc0135761, v48
	v_exp_f32_e32 v48, v48
	s_nop 0
	v_add_f32_e32 v48, 1.0, v48
	v_rcp_f32_e32 v114, v48
	v_mul_f32_e32 v48, 0x3d372713, v113
	v_mul_f32_e32 v48, v113, v48
	v_fma_f32 v48, v113, v48, v113
	v_mul_f32_e32 v48, 0xc0135761, v48
	v_exp_f32_e32 v48, v48
	s_nop 0
	v_add_f32_e32 v48, 1.0, v48
	v_rcp_f32_e32 v115, v48
	s_nop 0
	v_pk_mul_f32 v[112:113], v[112:113], v[114:115]
	v_pk_fma_f32 v[114:115], v[64:65], v[180:181], v[12:13]
	s_nop 0
	v_pk_fma_f32 v[114:115], v[80:81], v[190:191], v[114:115]
	s_nop 0
	v_pk_fma_f32 v[114:115], v[96:97], v[108:109], v[114:115]
	s_nop 0
	v_pk_mul_f32 v[112:113], v[114:115], v[112:113]
	v_pk_fma_f32 v[114:115], v[52:53], v[178:179], v[0:1]
	v_cvt_pk_f16_f32 v112, v112, v113
	v_pk_fma_f32 v[114:115], v[68:69], v[186:187], v[114:115]
	s_nop 0
	v_pk_fma_f32 v[114:115], v[84:85], v[100:101], v[114:115]
	s_nop 0
	v_mul_f32_e32 v48, 0x3d372713, v114
	v_mul_f32_e32 v48, v114, v48
	v_fma_f32 v48, v114, v48, v114
	v_mul_f32_e32 v48, 0xc0135761, v48
	v_exp_f32_e32 v48, v48
	s_nop 0
	v_add_f32_e32 v48, 1.0, v48
	v_rcp_f32_e32 v116, v48
	v_mul_f32_e32 v48, 0x3d372713, v115
	v_mul_f32_e32 v48, v115, v48
	v_fma_f32 v48, v115, v48, v115
	v_mul_f32_e32 v48, 0xc0135761, v48
	v_exp_f32_e32 v48, v48
	s_nop 0
	v_add_f32_e32 v48, 1.0, v48
	v_rcp_f32_e32 v117, v48
	s_nop 0
	v_pk_mul_f32 v[114:115], v[114:115], v[116:117]
	v_pk_fma_f32 v[116:117], v[60:61], v[176:177], v[8:9]
	s_nop 0
	v_pk_fma_f32 v[116:117], v[76:77], v[154:155], v[116:117]
	s_nop 0
	v_pk_fma_f32 v[116:117], v[92:93], v[104:105], v[116:117]
	s_nop 0
	v_pk_mul_f32 v[114:115], v[116:117], v[114:115]
	v_pk_fma_f32 v[116:117], v[58:59], v[174:175], v[6:7]
	v_cvt_pk_f16_f32 v114, v114, v115
	v_pk_fma_f32 v[116:117], v[74:75], v[162:163], v[116:117]
	s_nop 0
	v_pk_fma_f32 v[116:117], v[90:91], v[126:127], v[116:117]
	s_nop 0
	v_mul_f32_e32 v48, 0x3d372713, v116
	v_mul_f32_e32 v48, v116, v48
	v_fma_f32 v48, v116, v48, v116
	v_mul_f32_e32 v48, 0xc0135761, v48
	v_exp_f32_e32 v48, v48
	s_nop 0
	v_add_f32_e32 v48, 1.0, v48
	v_rcp_f32_e32 v118, v48
	v_mul_f32_e32 v48, 0x3d372713, v117
	v_mul_f32_e32 v48, v117, v48
	v_fma_f32 v48, v117, v48, v117
	v_mul_f32_e32 v48, 0xc0135761, v48
	v_exp_f32_e32 v48, v48
	s_nop 0
	v_add_f32_e32 v48, 1.0, v48
	v_rcp_f32_e32 v119, v48
	s_nop 0
	v_pk_mul_f32 v[116:117], v[116:117], v[118:119]
	v_pk_fma_f32 v[118:119], v[66:67], v[172:173], v[14:15]
	s_nop 0
	v_pk_fma_f32 v[118:119], v[82:83], v[158:159], v[118:119]
	s_nop 0
	v_pk_fma_f32 v[118:119], v[98:99], v[110:111], v[118:119]
	s_nop 0
	v_pk_mul_f32 v[116:117], v[118:119], v[116:117]
	s_nop 0
	v_cvt_pk_f16_f32 v113, v116, v117
	v_pk_fma_f32 v[116:117], v[54:55], v[170:171], v[2:3]
	s_nop 0
	v_pk_fma_f32 v[116:117], v[70:71], v[156:157], v[116:117]
	s_nop 0
	v_pk_fma_f32 v[116:117], v[86:87], v[102:103], v[116:117]
	s_nop 0
	v_mul_f32_e32 v48, 0x3d372713, v116
	v_mul_f32_e32 v48, v116, v48
	v_fma_f32 v48, v116, v48, v116
	v_mul_f32_e32 v48, 0xc0135761, v48
	v_exp_f32_e32 v48, v48
	s_nop 0
	v_add_f32_e32 v48, 1.0, v48
	v_rcp_f32_e32 v118, v48
	v_mul_f32_e32 v48, 0x3d372713, v117
	v_mul_f32_e32 v48, v117, v48
	v_fma_f32 v48, v117, v48, v117
	v_mul_f32_e32 v48, 0xc0135761, v48
	v_exp_f32_e32 v48, v48
	s_nop 0
	v_add_f32_e32 v48, 1.0, v48
	v_rcp_f32_e32 v119, v48
	v_add_u32_e32 v48, s51, v195
	v_pk_mul_f32 v[116:117], v[116:117], v[118:119]
	v_pk_fma_f32 v[118:119], v[62:63], v[160:161], v[10:11]
	s_nop 0
	v_pk_fma_f32 v[118:119], v[78:79], v[152:153], v[118:119]
	s_nop 0
	v_pk_fma_f32 v[118:119], v[94:95], v[106:107], v[118:119]
	s_nop 0
	v_pk_mul_f32 v[116:117], v[118:119], v[116:117]
	s_nop 0
	v_cvt_pk_f16_f32 v115, v116, v117
	v_add_co_u32_e32 v116, vcc, 0x4d1a3000, v184
	s_nop 1
	v_addc_co_u32_e32 v117, vcc, 0, v185, vcc
	global_store_dwordx4 v[116:117], v[112:115], off offset:3072
	s_nop 1
	v_add_u32_e32 v112, 6, v48
	v_cmp_lt_u32_e32 vcc, s97, v112
	s_and_saveexec_b64 s[0:1], vcc
	s_cbranch_execz .LBB0_1279
	v_add_co_u32_e32 v112, vcc, 0xffff8000, v50
	s_nop 1
	v_addc_co_u32_e32 v113, vcc, -1, v51, vcc
	global_store_dwordx4 v[112:113], v[124:127], off offset:-1040
	global_store_dwordx4 v[112:113], v[100:103], off offset:-1024
	v_add_co_u32_e32 v112, vcc, 0xffffb000, v50
	s_nop 1
	v_addc_co_u32_e32 v113, vcc, -1, v51, vcc
	global_store_dwordx4 v[112:113], v[108:111], off offset:-2064
	global_store_dwordx4 v[112:113], v[104:107], off offset:-2048
; DEVI float gelu_f(float x) { const float u = -2.302208198f * (x + 0.044715f * x * x * x); return x * __builtin_amdgcn_rcpf(1.f + __builtin_amdgcn_exp2f(u)); }
; DEVI void conv_gate_items(unsigned it_begin, unsigned it_end, unsigned it_step, const int rseg, const ConvP P) {
;     ...
;             for (int k = 0; k < 4; ++k) { const int r = r0 + k; const float mean = rsm[k] * (1.f / DM), rstd = __builtin_amdgcn_rsqf(rsq[k] * (1.f / DM) - mean * mean + 1e-5f);
;                 const f4 cg0 = ((f4){(float)ra[k][0], (float)ra[k][1], (float)ra[k][2], (float)ra[k][3]} - cg0_ * mean) * rstd + dg0_, cg1 = ((f4){(float)ra[k][4], (float)ra[k][5], (float)ra[k][6], (float)ra[k][7]} - cg1_ * mean) * rstd + dg1_;
;                 const f4 cv0 = ((f4){(float)rc[k][0], (float)rc[k][1], (float)rc[k][2], (float)rc[k][3]} - cv0_ * mean) * rstd + dv0_, cv1 = ((f4){(float)rc[k][4], (float)rc[k][5], (float)rc[k][6], (float)rc[k][7]} - cv1_ * mean) * rstd + dv1_;
;                 const f4 g0 = bg0 + ag0 * wg0[0] + bg0_ * wg0[1] + cg0 * wg0[2], g1 = bg1 + ag1 * wg1[0] + bg1_ * wg1[1] + cg1 * wg1[2];
;                 const f4 v0 = bv0 + av0 * wv0[0] + bv0_ * wv0[1] + cv0 * wv0[2], v1 = bv1 + av1 * wv1[0] + bv1_ * wv1[1] + cv1 * wv1[2];
;                 h8 o;
; #pragma unroll
;                 for (int e = 0; e < 4; ++e) { o[e] = (h16)(gelu_f(g0[e]) * v0[e]); o[4 + e] = (h16)(gelu_f(g1[e]) * v1[e]); }
;                 __builtin_nontemporal_store(o, (h8*)(ar + (size_t)r * DFF));
;                 const int t = t0 + r;
;                 if (t >= T - 2) { float* so = P.pfc + (samp ? P.sdelta + ((size_t)bb * 2 + (t - (T - 2))) * DFF2 : ((size_t)(row0 >> 11) * 2 + (t - (T - 2))) * DFF2) + j0;
;                     *(f4*)so = cg0; *(f4*)(so + 4) = cg1; *(f4*)(so + DFF) = cv0; *(f4*)(so + DFF + 4) = cv1; }
.LBB0_1279:
	s_or_b64 exec, exec, s[0:1]
	v_pk_mul_f32 v[128:129], v[142:143], s[82:83] op_sel_hi:[1,0]
	v_cvt_f32_f16_sdwa v121, v132 dst_sel:DWORD dst_unused:UNUSED_PAD src0_sel:WORD_1
	v_fma_f32 v112, -v128, v128, v129
	v_add_f32_e32 v112, 0x3727c5ac, v112
	v_cvt_f32_f16_e32 v120, v132
	v_cvt_f32_f16_sdwa v123, v133 dst_sel:DWORD dst_unused:UNUSED_PAD src0_sel:WORD_1
	v_cvt_f32_f16_e32 v122, v133
	v_cvt_f32_f16_sdwa v133, v135 dst_sel:DWORD dst_unused:UNUSED_PAD src0_sel:WORD_1
	v_cvt_f32_f16_e32 v132, v135
	v_rsq_f32_e32 v140, v112
	v_cvt_f32_f16_sdwa v113, v136 dst_sel:DWORD dst_unused:UNUSED_PAD src0_sel:WORD_1
	v_cvt_f32_f16_e32 v112, v136
	v_cvt_f32_f16_sdwa v115, v137 dst_sel:DWORD dst_unused:UNUSED_PAD src0_sel:WORD_1
	v_cvt_f32_f16_e32 v114, v137
	v_cvt_f32_f16_sdwa v117, v138 dst_sel:DWORD dst_unused:UNUSED_PAD src0_sel:WORD_1
	v_cvt_f32_f16_e32 v116, v138
	v_cvt_f32_f16_sdwa v119, v139 dst_sel:DWORD dst_unused:UNUSED_PAD src0_sel:WORD_1
	v_cvt_f32_f16_e32 v118, v139
	v_cvt_f32_f16_sdwa v131, v134 dst_sel:DWORD dst_unused:UNUSED_PAD src0_sel:WORD_1
	v_cvt_f32_f16_e32 v130, v134
	v_pk_fma_f32 v[132:133], v[26:27], v[128:129], v[132:133] op_sel_hi:[1,0,1]
	v_pk_fma_f32 v[114:115], v[22:23], v[128:129], v[114:115] op_sel_hi:[1,0,1]
	v_pk_fma_f32 v[112:113], v[20:21], v[128:129], v[112:113] op_sel_hi:[1,0,1] neg_lo:[1,0,0] neg_hi:[1,0,0]
	v_pk_fma_f32 v[118:119], v[18:19], v[128:129], v[118:119] op_sel_hi:[1,0,1]
	v_pk_fma_f32 v[116:117], v[16:17], v[128:129], v[116:117] op_sel_hi:[1,0,1] neg_lo:[1,0,0] neg_hi:[1,0,0]
	v_pk_fma_f32 v[122:123], v[30:31], v[128:129], v[122:123] op_sel_hi:[1,0,1]
	v_pk_fma_f32 v[120:121], v[28:29], v[128:129], v[120:121] op_sel_hi:[1,0,1] neg_lo:[1,0,0] neg_hi:[1,0,0]
	v_pk_fma_f32 v[128:129], v[24:25], v[128:129], v[130:131] op_sel_hi:[1,0,1] neg_lo:[1,0,0] neg_hi:[1,0,0]
	v_pk_fma_f32 v[130:131], v[132:133], v[140:141], v[42:43] op_sel_hi:[1,0,1]
	v_pk_fma_f32 v[132:133], v[56:57], v[188:189], v[4:5]
	v_pk_fma_f32 v[112:113], v[112:113], v[140:141], v[36:37] op_sel_hi:[1,0,1]
	v_pk_fma_f32 v[132:133], v[72:73], v[124:125], v[132:133]
	v_pk_fma_f32 v[120:121], v[120:121], v[140:141], v[44:45] op_sel_hi:[1,0,1]
	v_pk_fma_f32 v[132:133], v[88:89], v[112:113], v[132:133]
	v_pk_fma_f32 v[116:117], v[116:117], v[140:141], v[32:33] op_sel_hi:[1,0,1]
	v_mul_f32_e32 v134, 0x3d372713, v132
	v_mul_f32_e32 v135, 0x3d372713, v133
	v_mul_f32_e32 v134, v132, v134
	v_mul_f32_e32 v135, v133, v135
	v_fma_f32 v134, v132, v134, v132
	v_fma_f32 v135, v133, v135, v133
	v_mul_f32_e32 v134, 0xc0135761, v134
	v_mul_f32_e32 v135, 0xc0135761, v135
	v_exp_f32_e32 v134, v134
	v_exp_f32_e32 v135, v135
	v_pk_fma_f32 v[128:129], v[128:129], v[140:141], v[40:41] op_sel_hi:[1,0,1]
	v_pk_fma_f32 v[114:115], v[114:115], v[140:141], v[38:39] op_sel_hi:[1,0,1]
	v_add_f32_e32 v134, 1.0, v134
	v_add_f32_e32 v135, 1.0, v135
	v_rcp_f32_e32 v134, v134
	v_rcp_f32_e32 v135, v135
	v_pk_fma_f32 v[122:123], v[122:123], v[140:141], v[46:47] op_sel_hi:[1,0,1]
	v_pk_fma_f32 v[118:119], v[118:119], v[140:141], v[34:35] op_sel_hi:[1,0,1]
	v_add_u32_e32 v48, 7, v48
	v_pk_mul_f32 v[132:133], v[132:133], v[134:135]
	v_pk_fma_f32 v[134:135], v[64:65], v[190:191], v[12:13]
	s_nop 0
	v_pk_fma_f32 v[134:135], v[80:81], v[108:109], v[134:135]
	s_nop 0
	v_pk_fma_f32 v[134:135], v[96:97], v[120:121], v[134:135]
	s_nop 0
	v_pk_mul_f32 v[132:133], v[134:135], v[132:133]
	v_pk_fma_f32 v[134:135], v[52:53], v[186:187], v[0:1]
	v_cvt_pk_f16_f32 v132, v132, v133
	v_pk_fma_f32 v[134:135], v[68:69], v[100:101], v[134:135]
	s_nop 0
	v_pk_fma_f32 v[134:135], v[84:85], v[116:117], v[134:135]
	s_nop 0
	v_mul_f32_e32 v133, 0x3d372713, v134
	v_mul_f32_e32 v133, v134, v133
	v_fma_f32 v133, v134, v133, v134
	v_mul_f32_e32 v133, 0xc0135761, v133
	v_exp_f32_e32 v133, v133
	s_nop 0
	v_add_f32_e32 v133, 1.0, v133
	v_rcp_f32_e32 v136, v133
	v_mul_f32_e32 v133, 0x3d372713, v135
	v_mul_f32_e32 v133, v135, v133
	v_fma_f32 v133, v135, v133, v135
	v_mul_f32_e32 v133, 0xc0135761, v133
	v_exp_f32_e32 v133, v133
	s_nop 0
	v_add_f32_e32 v133, 1.0, v133
	v_rcp_f32_e32 v137, v133
	s_nop 0
	v_pk_mul_f32 v[134:135], v[134:135], v[136:137]
	v_pk_fma_f32 v[136:137], v[60:61], v[154:155], v[8:9]
	s_nop 0
	v_pk_fma_f32 v[136:137], v[76:77], v[104:105], v[136:137]
	s_nop 0
	v_pk_fma_f32 v[136:137], v[92:93], v[128:129], v[136:137]
	s_nop 0
	v_pk_mul_f32 v[134:135], v[136:137], v[134:135]
	v_pk_fma_f32 v[136:137], v[58:59], v[162:163], v[6:7]
	v_cvt_pk_f16_f32 v134, v134, v135
	v_pk_fma_f32 v[136:137], v[74:75], v[126:127], v[136:137]
	s_nop 0
	v_pk_fma_f32 v[136:137], v[90:91], v[114:115], v[136:137]
	s_nop 0
	v_mul_f32_e32 v133, 0x3d372713, v136
	v_mul_f32_e32 v133, v136, v133
	v_fma_f32 v133, v136, v133, v136
	v_mul_f32_e32 v133, 0xc0135761, v133
	v_exp_f32_e32 v133, v133
	s_nop 0
	v_add_f32_e32 v133, 1.0, v133
	v_rcp_f32_e32 v138, v133
	v_mul_f32_e32 v133, 0x3d372713, v137
	v_mul_f32_e32 v133, v137, v133
	v_fma_f32 v133, v137, v133, v137
	v_mul_f32_e32 v133, 0xc0135761, v133
	v_exp_f32_e32 v133, v133
	s_nop 0
	v_add_f32_e32 v133, 1.0, v133
	v_rcp_f32_e32 v139, v133
	s_nop 0
	v_pk_mul_f32 v[136:137], v[136:137], v[138:139]
	v_pk_fma_f32 v[138:139], v[66:67], v[158:159], v[14:15]
	s_nop 0
	v_pk_fma_f32 v[138:139], v[82:83], v[110:111], v[138:139]
	s_nop 0
	v_pk_fma_f32 v[138:139], v[98:99], v[122:123], v[138:139]
	s_nop 0
	v_pk_mul_f32 v[136:137], v[138:139], v[136:137]
	s_nop 0
	v_cvt_pk_f16_f32 v133, v136, v137
	v_pk_fma_f32 v[136:137], v[54:55], v[156:157], v[2:3]
	s_nop 0
	v_pk_fma_f32 v[136:137], v[70:71], v[102:103], v[136:137]
	s_nop 0
	v_pk_fma_f32 v[136:137], v[86:87], v[118:119], v[136:137]
	s_nop 0
	v_mul_f32_e32 v135, 0x3d372713, v136
	v_mul_f32_e32 v135, v136, v135
	v_fma_f32 v135, v136, v135, v136
	v_mul_f32_e32 v135, 0xc0135761, v135
	v_exp_f32_e32 v135, v135
	s_nop 0
	v_add_f32_e32 v135, 1.0, v135
	v_rcp_f32_e32 v138, v135
	v_mul_f32_e32 v135, 0x3d372713, v137
	v_mul_f32_e32 v135, v137, v135
	v_fma_f32 v135, v137, v135, v137
	v_mul_f32_e32 v135, 0xc0135761, v135
	v_exp_f32_e32 v135, v135
	s_nop 0
	v_add_f32_e32 v135, 1.0, v135
	v_rcp_f32_e32 v139, v135
	s_nop 0
	v_pk_mul_f32 v[136:137], v[136:137], v[138:139]
	v_pk_fma_f32 v[138:139], v[62:63], v[152:153], v[10:11]
	s_nop 0
	v_pk_fma_f32 v[138:139], v[78:79], v[106:107], v[138:139]
	s_nop 0
	v_pk_fma_f32 v[138:139], v[94:95], v[130:131], v[138:139]
	s_nop 0
	v_pk_mul_f32 v[136:137], v[138:139], v[136:137]
	s_nop 0
	v_cvt_pk_f16_f32 v135, v136, v137
	v_add_co_u32_e32 v136, vcc, 0x4d1a5000, v184
	s_nop 1
	v_addc_co_u32_e32 v137, vcc, 0, v185, vcc
	v_cmp_lt_u32_e32 vcc, s97, v48
	global_store_dwordx4 v[136:137], v[132:135], off offset:512
	s_and_saveexec_b64 s[0:1], vcc
	s_cbranch_execz .LBB0_1276
; DEVI void conv_gate_items(unsigned it_begin, unsigned it_end, unsigned it_step, const int rseg, const ConvP P) {
;     ...
;                 if (t >= T - 2) { float* so = P.pfc + (samp ? P.sdelta + ((size_t)bb * 2 + (t - (T - 2))) * DFF2 : ((size_t)(row0 >> 11) * 2 + (t - (T - 2))) * DFF2) + j0;
;                     *(f4*)so = cg0; *(f4*)(so + 4) = cg1; *(f4*)(so + DFF) = cv0; *(f4*)(so + DFF + 4) = cv1; }
;                 ag0 = bg0_; ag1 = bg1_; av0 = bv0_; av1 = bv1_; bg0_ = cg0; bg1_ = cg1; bv0_ = cv0; bv1_ = cv1; } } }
	v_add_co_u32_e32 v132, vcc, 0xffffe000, v50
	s_nop 1
	v_addc_co_u32_e32 v133, vcc, -1, v51, vcc
	global_store_dwordx4 v[132:133], v[112:115], off offset:-3088
	global_store_dwordx4 v[132:133], v[116:119], off offset:-3072
	global_store_dwordx4 v[50:51], v[120:123], off offset:-16
	global_store_dwordx4 v[50:51], v[128:131], off
	s_branch .LBB0_1276
